# previous best plus gemm_in tile map where co-resident workgroups share the B tile, and scan workgroups bypass the drained attention queue after the scan
# baseline (speedup 1.0000x reference)
.Lscan_skip_first:
	s_waitcnt lgkmcnt(6)
	v_pk_mul_f32 v[102:103], v[52:53], v[56:57]
	v_pk_fma_f32 v[102:103], v[54:55], v[58:59], v[102:103]
	v_pk_mul_f32 v[104:105], v[68:69], v[76:77] op_sel_hi:[1,0]
	v_add_f32_e32 v102, v102, v103
	v_pk_mul_f32 v[106:107], v[70:71], v[76:77] op_sel_hi:[1,0]
	ds_read_b128 v[136:139], v129 offset:2688
	v_add_f32_dpp v102, v102, v102 quad_perm:[1,0,3,2] row_mask:0xf bank_mask:0xf bound_ctrl:1
	v_pk_fma_f32 v[104:105], v[52:53], v[60:61], v[104:105]
	ds_read_b128 v[140:143], v129 offset:2944
	v_add_f32_dpp v102, v102, v102 quad_perm:[2,3,0,1] row_mask:0xf bank_mask:0xf bound_ctrl:1
	v_pk_fma_f32 v[106:107], v[54:55], v[62:63], v[106:107]
	ds_read_b128 v[144:147], v129 offset:3200
	v_add_f32_dpp v102, v102, v102 row_half_mirror row_mask:0xf bank_mask:0xf bound_ctrl:1
	ds_read_b128 v[148:151], v129 offset:3456
	ds_read_b128 v[152:155], v129 offset:3712
	v_add_f32_dpp v102, v102, v102 row_mirror row_mask:0xf bank_mask:0xf bound_ctrl:1
	v_pk_fma_f32 v[52:53], v[64:65], v[102:103], v[104:105] op_sel_hi:[1,0,1] neg_lo:[0,1,0] neg_hi:[0,1,0]
	v_pk_fma_f32 v[54:55], v[66:67], v[102:103], v[106:107] op_sel_hi:[1,0,1] neg_lo:[0,1,0] neg_hi:[0,1,0]
	ds_read_b32 v156, v131 offset:3968
	s_waitcnt lgkmcnt(6)
	v_pk_mul_f32 v[102:103], v[52:53], v[80:81]
	v_pk_mul_f32 v[108:109], v[74:75], v[54:55]
	v_pk_fma_f32 v[102:103], v[54:55], v[82:83], v[102:103]
	v_pk_fma_f32 v[108:109], v[72:73], v[52:53], v[108:109]
	v_pk_mul_f32 v[104:105], v[92:93], v[100:101] op_sel_hi:[1,0]
	v_add_f32_e32 v102, v102, v103
	v_add_f32_e32 v214, v108, v109
	v_pk_mul_f32 v[106:107], v[94:95], v[100:101] op_sel_hi:[1,0]
	v_add_f32_dpp v102, v102, v102 quad_perm:[1,0,3,2] row_mask:0xf bank_mask:0xf bound_ctrl:1
	v_pk_fma_f32 v[104:105], v[52:53], v[84:85], v[104:105]
	ds_read_b128 v[56:59], v129 offset:4032
	v_add_f32_dpp v102, v102, v102 quad_perm:[2,3,0,1] row_mask:0xf bank_mask:0xf bound_ctrl:1
	v_pk_fma_f32 v[106:107], v[54:55], v[86:87], v[106:107]
	ds_read_b128 v[60:63], v129 offset:4288
	v_add_f32_dpp v102, v102, v102 row_half_mirror row_mask:0xf bank_mask:0xf bound_ctrl:1
	ds_read_b128 v[64:67], v129 offset:4544
	ds_read_b128 v[68:71], v129 offset:4800
	v_add_f32_dpp v102, v102, v102 row_mirror row_mask:0xf bank_mask:0xf bound_ctrl:1
	v_pk_fma_f32 v[52:53], v[88:89], v[102:103], v[104:105] op_sel_hi:[1,0,1] neg_lo:[0,1,0] neg_hi:[0,1,0]
	v_pk_fma_f32 v[54:55], v[90:91], v[102:103], v[106:107] op_sel_hi:[1,0,1] neg_lo:[0,1,0] neg_hi:[0,1,0]
	ds_read_b128 v[72:75], v129 offset:5056
	ds_read_b32 v76, v131 offset:5312
	s_waitcnt lgkmcnt(6)
	v_pk_mul_f32 v[102:103], v[52:53], v[136:137]
	v_pk_mul_f32 v[108:109], v[98:99], v[54:55]
	v_pk_fma_f32 v[102:103], v[54:55], v[138:139], v[102:103]
	v_pk_fma_f32 v[108:109], v[96:97], v[52:53], v[108:109]
	v_pk_mul_f32 v[104:105], v[148:149], v[156:157] op_sel_hi:[1,0]
	v_add_f32_e32 v102, v102, v103
	v_add_f32_e32 v215, v108, v109
	v_pk_mul_f32 v[106:107], v[150:151], v[156:157] op_sel_hi:[1,0]
	v_add_f32_dpp v102, v102, v102 quad_perm:[1,0,3,2] row_mask:0xf bank_mask:0xf bound_ctrl:1
	v_pk_fma_f32 v[104:105], v[52:53], v[140:141], v[104:105]
	ds_read_b128 v[80:83], v129 offset:5376
	v_add_f32_dpp v102, v102, v102 quad_perm:[2,3,0,1] row_mask:0xf bank_mask:0xf bound_ctrl:1
	v_pk_fma_f32 v[106:107], v[54:55], v[142:143], v[106:107]
	ds_read_b128 v[84:87], v129 offset:5632
	v_add_f32_dpp v102, v102, v102 row_half_mirror row_mask:0xf bank_mask:0xf bound_ctrl:1
	ds_read_b128 v[88:91], v129 offset:5888
	ds_read_b128 v[92:95], v129 offset:6144
	v_add_f32_dpp v102, v102, v102 row_mirror row_mask:0xf bank_mask:0xf bound_ctrl:1
	v_pk_fma_f32 v[52:53], v[144:145], v[102:103], v[104:105] op_sel_hi:[1,0,1] neg_lo:[0,1,0] neg_hi:[0,1,0]
	v_pk_fma_f32 v[54:55], v[146:147], v[102:103], v[106:107] op_sel_hi:[1,0,1] neg_lo:[0,1,0] neg_hi:[0,1,0]
	ds_read_b128 v[96:99], v129 offset:6400
	ds_read_b32 v100, v131 offset:6656
	s_waitcnt lgkmcnt(6)
	v_pk_mul_f32 v[102:103], v[52:53], v[56:57]
	v_pk_mul_f32 v[108:109], v[154:155], v[54:55]
	v_pk_fma_f32 v[102:103], v[54:55], v[58:59], v[102:103]
	v_pk_fma_f32 v[108:109], v[152:153], v[52:53], v[108:109]
	v_pk_mul_f32 v[104:105], v[68:69], v[76:77] op_sel_hi:[1,0]
	v_add_f32_e32 v102, v102, v103
	v_add_f32_e32 v216, v108, v109
	v_pk_mul_f32 v[106:107], v[70:71], v[76:77] op_sel_hi:[1,0]
	v_add_f32_dpp v102, v102, v102 quad_perm:[1,0,3,2] row_mask:0xf bank_mask:0xf bound_ctrl:1
	v_pk_fma_f32 v[104:105], v[52:53], v[60:61], v[104:105]
	ds_read_b128 v[136:139], v129 offset:6720
	v_add_f32_dpp v102, v102, v102 quad_perm:[2,3,0,1] row_mask:0xf bank_mask:0xf bound_ctrl:1
	v_pk_fma_f32 v[106:107], v[54:55], v[62:63], v[106:107]
	ds_read_b128 v[140:143], v129 offset:6976
	v_add_f32_dpp v102, v102, v102 row_half_mirror row_mask:0xf bank_mask:0xf bound_ctrl:1
	ds_read_b128 v[144:147], v129 offset:7232
	ds_read_b128 v[148:151], v129 offset:7488
	v_add_f32_dpp v102, v102, v102 row_mirror row_mask:0xf bank_mask:0xf bound_ctrl:1
	v_pk_fma_f32 v[52:53], v[64:65], v[102:103], v[104:105] op_sel_hi:[1,0,1] neg_lo:[0,1,0] neg_hi:[0,1,0]
	v_pk_fma_f32 v[54:55], v[66:67], v[102:103], v[106:107] op_sel_hi:[1,0,1] neg_lo:[0,1,0] neg_hi:[0,1,0]
	ds_read_b128 v[152:155], v129 offset:7744
	ds_read_b32 v156, v131 offset:8000
	s_waitcnt lgkmcnt(6)
	v_pk_mul_f32 v[102:103], v[52:53], v[80:81]
	v_pk_mul_f32 v[108:109], v[74:75], v[54:55]
	v_pk_fma_f32 v[102:103], v[54:55], v[82:83], v[102:103]
	v_pk_fma_f32 v[108:109], v[72:73], v[52:53], v[108:109]
	v_pk_mul_f32 v[104:105], v[92:93], v[100:101] op_sel_hi:[1,0]
	v_add_f32_e32 v102, v102, v103
	v_add_f32_e32 v217, v108, v109
	v_pk_mul_f32 v[106:107], v[94:95], v[100:101] op_sel_hi:[1,0]
	v_add_f32_dpp v102, v102, v102 quad_perm:[1,0,3,2] row_mask:0xf bank_mask:0xf bound_ctrl:1
	v_pk_fma_f32 v[104:105], v[52:53], v[84:85], v[104:105]
	ds_read_b128 v[56:59], v129 offset:8064
	v_add_f32_dpp v102, v102, v102 quad_perm:[2,3,0,1] row_mask:0xf bank_mask:0xf bound_ctrl:1
	v_pk_fma_f32 v[106:107], v[54:55], v[86:87], v[106:107]
	ds_read_b128 v[60:63], v129 offset:8320
	v_add_f32_dpp v102, v102, v102 row_half_mirror row_mask:0xf bank_mask:0xf bound_ctrl:1
	ds_read_b128 v[64:67], v129 offset:8576
	ds_read_b128 v[68:71], v129 offset:8832
	v_add_f32_dpp v102, v102, v102 row_mirror row_mask:0xf bank_mask:0xf bound_ctrl:1
	v_pk_fma_f32 v[52:53], v[88:89], v[102:103], v[104:105] op_sel_hi:[1,0,1] neg_lo:[0,1,0] neg_hi:[0,1,0]
	v_pk_fma_f32 v[54:55], v[90:91], v[102:103], v[106:107] op_sel_hi:[1,0,1] neg_lo:[0,1,0] neg_hi:[0,1,0]
	ds_read_b128 v[72:75], v129 offset:9088
	ds_read_b32 v76, v131 offset:9344
	s_waitcnt lgkmcnt(6)
	v_pk_mul_f32 v[102:103], v[52:53], v[136:137]
	v_pk_mul_f32 v[108:109], v[98:99], v[54:55]
	v_pk_fma_f32 v[102:103], v[54:55], v[138:139], v[102:103]
	v_pk_fma_f32 v[108:109], v[96:97], v[52:53], v[108:109]
	v_pk_mul_f32 v[104:105], v[148:149], v[156:157] op_sel_hi:[1,0]
	v_add_f32_e32 v102, v102, v103
	v_add_f32_e32 v218, v108, v109
	v_pk_mul_f32 v[106:107], v[150:151], v[156:157] op_sel_hi:[1,0]
	v_add_f32_dpp v102, v102, v102 quad_perm:[1,0,3,2] row_mask:0xf bank_mask:0xf bound_ctrl:1
	v_pk_fma_f32 v[104:105], v[52:53], v[140:141], v[104:105]
	ds_read_b128 v[80:83], v129 offset:9408
	v_add_f32_dpp v102, v102, v102 quad_perm:[2,3,0,1] row_mask:0xf bank_mask:0xf bound_ctrl:1
	v_pk_fma_f32 v[106:107], v[54:55], v[142:143], v[106:107]
	ds_read_b128 v[84:87], v129 offset:9664
	v_add_f32_dpp v102, v102, v102 row_half_mirror row_mask:0xf bank_mask:0xf bound_ctrl:1
	ds_read_b128 v[88:91], v129 offset:9920
	ds_read_b128 v[92:95], v129 offset:10176
	v_add_f32_dpp v102, v102, v102 row_mirror row_mask:0xf bank_mask:0xf bound_ctrl:1
	v_pk_fma_f32 v[52:53], v[144:145], v[102:103], v[104:105] op_sel_hi:[1,0,1] neg_lo:[0,1,0] neg_hi:[0,1,0]
	v_pk_fma_f32 v[54:55], v[146:147], v[102:103], v[106:107] op_sel_hi:[1,0,1] neg_lo:[0,1,0] neg_hi:[0,1,0]
	ds_read_b128 v[96:99], v129 offset:10432
	ds_read_b32 v100, v131 offset:10688
	s_waitcnt lgkmcnt(6)
	v_pk_mul_f32 v[102:103], v[52:53], v[56:57]
	v_pk_mul_f32 v[108:109], v[154:155], v[54:55]
	v_pk_fma_f32 v[102:103], v[54:55], v[58:59], v[102:103]
	v_pk_fma_f32 v[108:109], v[152:153], v[52:53], v[108:109]
	v_pk_mul_f32 v[104:105], v[68:69], v[76:77] op_sel_hi:[1,0]
	v_add_f32_e32 v102, v102, v103
	v_add_f32_e32 v219, v108, v109
	v_pk_mul_f32 v[106:107], v[70:71], v[76:77] op_sel_hi:[1,0]
	v_add_f32_dpp v102, v102, v102 quad_perm:[1,0,3,2] row_mask:0xf bank_mask:0xf bound_ctrl:1
	v_pk_fma_f32 v[104:105], v[52:53], v[60:61], v[104:105]
	ds_read_b128 v[136:139], v129 offset:10752
	v_add_f32_dpp v102, v102, v102 quad_perm:[2,3,0,1] row_mask:0xf bank_mask:0xf bound_ctrl:1
	v_pk_fma_f32 v[106:107], v[54:55], v[62:63], v[106:107]
	ds_read_b128 v[140:143], v129 offset:11008
	v_add_f32_dpp v102, v102, v102 row_half_mirror row_mask:0xf bank_mask:0xf bound_ctrl:1
	ds_read_b128 v[144:147], v129 offset:11264
	ds_read_b128 v[148:151], v129 offset:11520
	v_add_f32_dpp v102, v102, v102 row_mirror row_mask:0xf bank_mask:0xf bound_ctrl:1
	v_pk_fma_f32 v[52:53], v[64:65], v[102:103], v[104:105] op_sel_hi:[1,0,1] neg_lo:[0,1,0] neg_hi:[0,1,0]
	v_pk_fma_f32 v[54:55], v[66:67], v[102:103], v[106:107] op_sel_hi:[1,0,1] neg_lo:[0,1,0] neg_hi:[0,1,0]
	ds_read_b128 v[152:155], v129 offset:11776
	ds_read_b32 v156, v131 offset:12032
	s_waitcnt lgkmcnt(6)
	v_pk_mul_f32 v[102:103], v[52:53], v[80:81]
	v_pk_mul_f32 v[108:109], v[74:75], v[54:55]
	v_pk_fma_f32 v[102:103], v[54:55], v[82:83], v[102:103]
	v_pk_fma_f32 v[108:109], v[72:73], v[52:53], v[108:109]
	v_pk_mul_f32 v[104:105], v[92:93], v[100:101] op_sel_hi:[1,0]
	v_add_f32_e32 v102, v102, v103
	v_add_f32_e32 v220, v108, v109
	v_pk_mul_f32 v[106:107], v[94:95], v[100:101] op_sel_hi:[1,0]
	v_add_f32_dpp v102, v102, v102 quad_perm:[1,0,3,2] row_mask:0xf bank_mask:0xf bound_ctrl:1
	v_pk_fma_f32 v[104:105], v[52:53], v[84:85], v[104:105]
	ds_read_b128 v[56:59], v129 offset:12096
	v_add_f32_dpp v102, v102, v102 quad_perm:[2,3,0,1] row_mask:0xf bank_mask:0xf bound_ctrl:1
	v_pk_fma_f32 v[106:107], v[54:55], v[86:87], v[106:107]
	ds_read_b128 v[60:63], v129 offset:12352
	v_add_f32_dpp v102, v102, v102 row_half_mirror row_mask:0xf bank_mask:0xf bound_ctrl:1
	ds_read_b128 v[64:67], v129 offset:12608
	ds_read_b128 v[68:71], v129 offset:12864
	v_add_f32_dpp v102, v102, v102 row_mirror row_mask:0xf bank_mask:0xf bound_ctrl:1
	v_pk_fma_f32 v[52:53], v[88:89], v[102:103], v[104:105] op_sel_hi:[1,0,1] neg_lo:[0,1,0] neg_hi:[0,1,0]
	v_pk_fma_f32 v[54:55], v[90:91], v[102:103], v[106:107] op_sel_hi:[1,0,1] neg_lo:[0,1,0] neg_hi:[0,1,0]
	ds_read_b128 v[72:75], v129 offset:13120
	ds_read_b32 v76, v131 offset:13376
	s_waitcnt lgkmcnt(6)
; __device__ __forceinline__ void scan_unit(const Params p, int u, char* smem) {
;     ...
;   f32x2 sA = {0.f, 0.f}, sB = {0.f, 0.f};
;   const int jg4 = jg * 4, vi = w * 4 + rw;
	v_pk_mul_f32 v[102:103], v[52:53], v[136:137]
	v_pk_mul_f32 v[108:109], v[98:99], v[54:55]
	v_pk_fma_f32 v[102:103], v[54:55], v[138:139], v[102:103]
	v_pk_fma_f32 v[108:109], v[96:97], v[52:53], v[108:109]
	v_pk_mul_f32 v[104:105], v[148:149], v[156:157] op_sel_hi:[1,0]
	v_add_f32_e32 v102, v102, v103
	v_add_f32_e32 v221, v108, v109
	v_pk_mul_f32 v[106:107], v[150:151], v[156:157] op_sel_hi:[1,0]
	v_add_f32_dpp v102, v102, v102 quad_perm:[1,0,3,2] row_mask:0xf bank_mask:0xf bound_ctrl:1
	v_pk_fma_f32 v[104:105], v[52:53], v[140:141], v[104:105]
	ds_read_b128 v[80:83], v129 offset:13440
	v_add_f32_dpp v102, v102, v102 quad_perm:[2,3,0,1] row_mask:0xf bank_mask:0xf bound_ctrl:1
	v_pk_fma_f32 v[106:107], v[54:55], v[142:143], v[106:107]
	ds_read_b128 v[84:87], v129 offset:13696
	v_add_f32_dpp v102, v102, v102 row_half_mirror row_mask:0xf bank_mask:0xf bound_ctrl:1
	ds_read_b128 v[88:91], v129 offset:13952
	ds_read_b128 v[92:95], v129 offset:14208
	v_add_f32_dpp v102, v102, v102 row_mirror row_mask:0xf bank_mask:0xf bound_ctrl:1
	v_pk_fma_f32 v[52:53], v[144:145], v[102:103], v[104:105] op_sel_hi:[1,0,1] neg_lo:[0,1,0] neg_hi:[0,1,0]
	v_pk_fma_f32 v[54:55], v[146:147], v[102:103], v[106:107] op_sel_hi:[1,0,1] neg_lo:[0,1,0] neg_hi:[0,1,0]
	ds_read_b128 v[96:99], v129 offset:14464
	ds_read_b32 v100, v131 offset:14720
	s_waitcnt vmcnt(11)
	ds_write_b128 v117, v[0:3] offset:21504
	s_waitcnt lgkmcnt(7)
	v_pk_mul_f32 v[102:103], v[52:53], v[56:57]
	v_pk_mul_f32 v[108:109], v[154:155], v[54:55]
	v_pk_fma_f32 v[102:103], v[54:55], v[58:59], v[102:103]
	v_pk_fma_f32 v[108:109], v[152:153], v[52:53], v[108:109]
	v_pk_mul_f32 v[104:105], v[68:69], v[76:77] op_sel_hi:[1,0]
	v_add_f32_e32 v102, v102, v103
	v_add_f32_e32 v222, v108, v109
	v_pk_mul_f32 v[106:107], v[70:71], v[76:77] op_sel_hi:[1,0]
	v_add_f32_dpp v102, v102, v102 quad_perm:[1,0,3,2] row_mask:0xf bank_mask:0xf bound_ctrl:1
	v_pk_fma_f32 v[104:105], v[52:53], v[60:61], v[104:105]
	ds_read_b128 v[136:139], v129 offset:14784
	v_add_f32_dpp v102, v102, v102 quad_perm:[2,3,0,1] row_mask:0xf bank_mask:0xf bound_ctrl:1
	v_pk_fma_f32 v[106:107], v[54:55], v[62:63], v[106:107]
	ds_read_b128 v[140:143], v129 offset:15040
	v_add_f32_dpp v102, v102, v102 row_half_mirror row_mask:0xf bank_mask:0xf bound_ctrl:1
	ds_read_b128 v[144:147], v129 offset:15296
	ds_read_b128 v[148:151], v129 offset:15552
	v_add_f32_dpp v102, v102, v102 row_mirror row_mask:0xf bank_mask:0xf bound_ctrl:1
	v_pk_fma_f32 v[52:53], v[64:65], v[102:103], v[104:105] op_sel_hi:[1,0,1] neg_lo:[0,1,0] neg_hi:[0,1,0]
	v_pk_fma_f32 v[54:55], v[66:67], v[102:103], v[106:107] op_sel_hi:[1,0,1] neg_lo:[0,1,0] neg_hi:[0,1,0]
	ds_read_b128 v[152:155], v129 offset:15808
	ds_read_b32 v156, v131 offset:16064
	s_waitcnt vmcnt(10)
	ds_write_b128 v119, v[4:7] offset:21504
	s_waitcnt lgkmcnt(8)
	v_pk_mul_f32 v[102:103], v[52:53], v[80:81]
	v_pk_mul_f32 v[108:109], v[74:75], v[54:55]
	v_pk_fma_f32 v[102:103], v[54:55], v[82:83], v[102:103]
	v_pk_fma_f32 v[108:109], v[72:73], v[52:53], v[108:109]
	v_pk_mul_f32 v[104:105], v[92:93], v[100:101] op_sel_hi:[1,0]
	v_add_f32_e32 v102, v102, v103
	v_add_f32_e32 v223, v108, v109
	v_pk_mul_f32 v[106:107], v[94:95], v[100:101] op_sel_hi:[1,0]
	v_add_f32_dpp v102, v102, v102 quad_perm:[1,0,3,2] row_mask:0xf bank_mask:0xf bound_ctrl:1
	v_pk_fma_f32 v[104:105], v[52:53], v[84:85], v[104:105]
	v_add_f32_dpp v172, v214, v214 row_mirror row_mask:0xf bank_mask:0x3
	v_add_f32_dpp v102, v102, v102 quad_perm:[2,3,0,1] row_mask:0xf bank_mask:0xf bound_ctrl:1
	v_pk_fma_f32 v[106:107], v[54:55], v[86:87], v[106:107]
	v_add_f32_dpp v172, v222, v222 row_mirror row_mask:0xf bank_mask:0xc
	v_add_f32_dpp v102, v102, v102 row_half_mirror row_mask:0xf bank_mask:0xf bound_ctrl:1
	ds_read_b128 v[56:59], v129 offset:16128
	ds_read_b128 v[60:63], v129 offset:16384
	v_add_f32_dpp v102, v102, v102 row_mirror row_mask:0xf bank_mask:0xf bound_ctrl:1
	v_pk_fma_f32 v[52:53], v[88:89], v[102:103], v[104:105] op_sel_hi:[1,0,1] neg_lo:[0,1,0] neg_hi:[0,1,0]
	v_pk_fma_f32 v[54:55], v[90:91], v[102:103], v[106:107] op_sel_hi:[1,0,1] neg_lo:[0,1,0] neg_hi:[0,1,0]
	ds_read_b128 v[64:67], v129 offset:16640
	ds_read_b128 v[68:71], v129 offset:16896
	ds_read_b128 v[72:75], v129 offset:17152
	ds_read_b32 v76, v131 offset:17408
	s_waitcnt vmcnt(9)
	ds_write_b128 v121, v[8:11] offset:21504
	s_waitcnt lgkmcnt(8)
	v_pk_mul_f32 v[102:103], v[52:53], v[136:137]
	v_pk_mul_f32 v[108:109], v[98:99], v[54:55]
	v_pk_fma_f32 v[102:103], v[54:55], v[138:139], v[102:103]
	v_pk_fma_f32 v[108:109], v[96:97], v[52:53], v[108:109]
	v_pk_mul_f32 v[104:105], v[148:149], v[156:157] op_sel_hi:[1,0]
	v_add_f32_e32 v102, v102, v103
	v_add_f32_e32 v224, v108, v109
	v_pk_mul_f32 v[106:107], v[150:151], v[156:157] op_sel_hi:[1,0]
	v_add_f32_dpp v102, v102, v102 quad_perm:[1,0,3,2] row_mask:0xf bank_mask:0xf bound_ctrl:1
	v_pk_fma_f32 v[104:105], v[52:53], v[140:141], v[104:105]
	v_add_f32_dpp v173, v215, v215 row_mirror row_mask:0xf bank_mask:0x3
	v_add_f32_dpp v102, v102, v102 quad_perm:[2,3,0,1] row_mask:0xf bank_mask:0xf bound_ctrl:1
	v_pk_fma_f32 v[106:107], v[54:55], v[142:143], v[106:107]
	v_add_f32_dpp v173, v223, v223 row_mirror row_mask:0xf bank_mask:0xc
	v_add_f32_dpp v102, v102, v102 row_half_mirror row_mask:0xf bank_mask:0xf bound_ctrl:1
	ds_read_b128 v[80:83], v129 offset:17472
	ds_read_b128 v[84:87], v129 offset:17728
	v_add_f32_dpp v102, v102, v102 row_mirror row_mask:0xf bank_mask:0xf bound_ctrl:1
	v_pk_fma_f32 v[52:53], v[144:145], v[102:103], v[104:105] op_sel_hi:[1,0,1] neg_lo:[0,1,0] neg_hi:[0,1,0]
	v_pk_fma_f32 v[54:55], v[146:147], v[102:103], v[106:107] op_sel_hi:[1,0,1] neg_lo:[0,1,0] neg_hi:[0,1,0]
	ds_read_b128 v[88:91], v129 offset:17984
	ds_read_b128 v[92:95], v129 offset:18240
	ds_read_b128 v[96:99], v129 offset:18496
	ds_read_b32 v100, v131 offset:18752
	s_waitcnt vmcnt(8)
; __device__ __forceinline__ void scan_unit(const Params p, int u, char* smem) {
;     ...
;   f32x2 sA = {0.f, 0.f}, sB = {0.f, 0.f};
;   const int jg4 = jg * 4, vi = w * 4 + rw;
	ds_write_b128 v123, v[12:15] offset:21504
	s_waitcnt lgkmcnt(8)
	v_pk_mul_f32 v[102:103], v[52:53], v[56:57]
	v_pk_mul_f32 v[108:109], v[154:155], v[54:55]
	v_pk_fma_f32 v[102:103], v[54:55], v[58:59], v[102:103]
	v_pk_fma_f32 v[108:109], v[152:153], v[52:53], v[108:109]
	v_pk_mul_f32 v[104:105], v[68:69], v[76:77] op_sel_hi:[1,0]
	v_add_f32_e32 v102, v102, v103
	v_add_f32_e32 v225, v108, v109
	v_pk_mul_f32 v[106:107], v[70:71], v[76:77] op_sel_hi:[1,0]
	v_add_f32_dpp v102, v102, v102 quad_perm:[1,0,3,2] row_mask:0xf bank_mask:0xf bound_ctrl:1
	v_pk_fma_f32 v[104:105], v[52:53], v[60:61], v[104:105]
	v_add_f32_dpp v174, v216, v216 row_mirror row_mask:0xf bank_mask:0x3
	v_add_f32_dpp v102, v102, v102 quad_perm:[2,3,0,1] row_mask:0xf bank_mask:0xf bound_ctrl:1
	v_pk_fma_f32 v[106:107], v[54:55], v[62:63], v[106:107]
	v_add_f32_dpp v174, v224, v224 row_mirror row_mask:0xf bank_mask:0xc
	v_add_f32_dpp v102, v102, v102 row_half_mirror row_mask:0xf bank_mask:0xf bound_ctrl:1
	ds_read_b128 v[136:139], v129 offset:18816
	ds_read_b128 v[140:143], v129 offset:19072
	v_add_f32_dpp v102, v102, v102 row_mirror row_mask:0xf bank_mask:0xf bound_ctrl:1
	v_pk_fma_f32 v[52:53], v[64:65], v[102:103], v[104:105] op_sel_hi:[1,0,1] neg_lo:[0,1,0] neg_hi:[0,1,0]
	v_pk_fma_f32 v[54:55], v[66:67], v[102:103], v[106:107] op_sel_hi:[1,0,1] neg_lo:[0,1,0] neg_hi:[0,1,0]
	ds_read_b128 v[144:147], v129 offset:19328
	ds_read_b128 v[148:151], v129 offset:19584
	ds_read_b128 v[152:155], v129 offset:19840
	ds_read_b32 v156, v131 offset:20096
	s_waitcnt vmcnt(7)
	ds_write_b128 v125, v[16:19] offset:21504
	s_waitcnt lgkmcnt(8)
	v_pk_mul_f32 v[102:103], v[52:53], v[80:81]
	v_pk_mul_f32 v[108:109], v[74:75], v[54:55]
	v_pk_fma_f32 v[102:103], v[54:55], v[82:83], v[102:103]
	v_pk_fma_f32 v[108:109], v[72:73], v[52:53], v[108:109]
	v_pk_mul_f32 v[104:105], v[92:93], v[100:101] op_sel_hi:[1,0]
	v_add_f32_e32 v102, v102, v103
	v_add_f32_e32 v226, v108, v109
	v_pk_mul_f32 v[106:107], v[94:95], v[100:101] op_sel_hi:[1,0]
	v_add_f32_dpp v102, v102, v102 quad_perm:[1,0,3,2] row_mask:0xf bank_mask:0xf bound_ctrl:1
	v_pk_fma_f32 v[104:105], v[52:53], v[84:85], v[104:105]
	v_add_f32_dpp v175, v217, v217 row_mirror row_mask:0xf bank_mask:0x3
	v_add_f32_dpp v102, v102, v102 quad_perm:[2,3,0,1] row_mask:0xf bank_mask:0xf bound_ctrl:1
	v_pk_fma_f32 v[106:107], v[54:55], v[86:87], v[106:107]
	v_add_f32_dpp v175, v225, v225 row_mirror row_mask:0xf bank_mask:0xc
	v_add_f32_dpp v102, v102, v102 row_half_mirror row_mask:0xf bank_mask:0xf bound_ctrl:1
	ds_read_b128 v[56:59], v129 offset:20160
	ds_read_b128 v[60:63], v129 offset:20416
	v_add_f32_dpp v102, v102, v102 row_mirror row_mask:0xf bank_mask:0xf bound_ctrl:1
	v_pk_fma_f32 v[52:53], v[88:89], v[102:103], v[104:105] op_sel_hi:[1,0,1] neg_lo:[0,1,0] neg_hi:[0,1,0]
	v_pk_fma_f32 v[54:55], v[90:91], v[102:103], v[106:107] op_sel_hi:[1,0,1] neg_lo:[0,1,0] neg_hi:[0,1,0]
	ds_read_b128 v[64:67], v129 offset:20672
	ds_read_b128 v[68:71], v129 offset:20928
	ds_read_b128 v[160:163], v129 offset:21184
	ds_read_b32 v76, v131 offset:21440
	s_waitcnt vmcnt(6)
	ds_write_b128 v127, v[20:23] offset:21504
	s_waitcnt lgkmcnt(8)
	v_pk_mul_f32 v[102:103], v[52:53], v[136:137]
	v_pk_mul_f32 v[108:109], v[98:99], v[54:55]
	v_pk_fma_f32 v[102:103], v[54:55], v[138:139], v[102:103]
	v_pk_fma_f32 v[108:109], v[96:97], v[52:53], v[108:109]
	v_pk_mul_f32 v[104:105], v[148:149], v[156:157] op_sel_hi:[1,0]
	v_add_f32_e32 v102, v102, v103
	v_add_f32_e32 v227, v108, v109
	v_pk_mul_f32 v[106:107], v[150:151], v[156:157] op_sel_hi:[1,0]
	v_add_f32_dpp v102, v102, v102 quad_perm:[1,0,3,2] row_mask:0xf bank_mask:0xf bound_ctrl:1
	v_pk_fma_f32 v[104:105], v[52:53], v[140:141], v[104:105]
	v_add_f32_dpp v176, v218, v218 row_mirror row_mask:0xf bank_mask:0x3
	v_add_f32_dpp v102, v102, v102 quad_perm:[2,3,0,1] row_mask:0xf bank_mask:0xf bound_ctrl:1
	v_pk_fma_f32 v[106:107], v[54:55], v[142:143], v[106:107]
	v_add_f32_dpp v176, v226, v226 row_mirror row_mask:0xf bank_mask:0xc
	v_add_f32_dpp v102, v102, v102 row_half_mirror row_mask:0xf bank_mask:0xf bound_ctrl:1
	s_nop 0
	s_nop 0
	v_add_f32_dpp v102, v102, v102 row_mirror row_mask:0xf bank_mask:0xf bound_ctrl:1
	v_pk_fma_f32 v[52:53], v[144:145], v[102:103], v[104:105] op_sel_hi:[1,0,1] neg_lo:[0,1,0] neg_hi:[0,1,0]
	v_pk_fma_f32 v[54:55], v[146:147], v[102:103], v[106:107] op_sel_hi:[1,0,1] neg_lo:[0,1,0] neg_hi:[0,1,0]
	s_waitcnt lgkmcnt(1)
	v_pk_mul_f32 v[102:103], v[52:53], v[56:57]
	v_pk_mul_f32 v[108:109], v[154:155], v[54:55]
	v_pk_fma_f32 v[102:103], v[54:55], v[58:59], v[102:103]
	v_pk_fma_f32 v[108:109], v[152:153], v[52:53], v[108:109]
	v_pk_mul_f32 v[104:105], v[68:69], v[76:77] op_sel_hi:[1,0]
	v_add_f32_e32 v102, v102, v103
	v_add_f32_e32 v228, v108, v109
	v_pk_mul_f32 v[106:107], v[70:71], v[76:77] op_sel_hi:[1,0]
	v_add_f32_dpp v102, v102, v102 quad_perm:[1,0,3,2] row_mask:0xf bank_mask:0xf bound_ctrl:1
	v_pk_fma_f32 v[104:105], v[52:53], v[60:61], v[104:105]
	v_add_f32_dpp v177, v219, v219 row_mirror row_mask:0xf bank_mask:0x3
	v_add_f32_dpp v102, v102, v102 quad_perm:[2,3,0,1] row_mask:0xf bank_mask:0xf bound_ctrl:1
	v_pk_fma_f32 v[106:107], v[54:55], v[62:63], v[106:107]
	v_add_f32_dpp v177, v227, v227 row_mirror row_mask:0xf bank_mask:0xc
	v_add_f32_dpp v102, v102, v102 row_half_mirror row_mask:0xf bank_mask:0xf bound_ctrl:1
	v_add_f32_dpp v180, v172, v172 row_half_mirror row_mask:0xf bank_mask:0x5
	s_nop 0
	v_add_f32_dpp v102, v102, v102 row_mirror row_mask:0xf bank_mask:0xf bound_ctrl:1
	v_add_f32_dpp v180, v176, v176 row_half_mirror row_mask:0xf bank_mask:0xa
	v_pk_fma_f32 v[52:53], v[64:65], v[102:103], v[104:105] op_sel_hi:[1,0,1] neg_lo:[0,1,0] neg_hi:[0,1,0]
	v_pk_fma_f32 v[54:55], v[66:67], v[102:103], v[106:107] op_sel_hi:[1,0,1] neg_lo:[0,1,0] neg_hi:[0,1,0]
	s_waitcnt lgkmcnt(0)
	s_barrier
	ds_read_b128 v[56:59], v129 offset:21504
	ds_read_b128 v[60:63], v129 offset:21760
	ds_read_b128 v[64:67], v129 offset:22016
	ds_read_b128 v[68:71], v129 offset:22272
	ds_read_b128 v[72:75], v129 offset:22528
	ds_read_b32 v76, v131 offset:22784
	ds_read_b128 v[80:83], v129 offset:22848
	ds_read_b128 v[84:87], v129 offset:23104
	ds_read_b128 v[88:91], v129 offset:23360
	ds_read_b128 v[92:95], v129 offset:23616
	ds_read_b128 v[96:99], v129 offset:23872
	ds_read_b32 v100, v131 offset:24128
	s_min_u32 s3, s2, 0x1fc
	s_add_i32 s3, s3, 3
	s_mul_i32 s3, s3, s0
	v_add_u32_e32 v112, s3, v168
	v_add_u32_e32 v113, s3, v116
	v_add_u32_e32 v114, s3, v118
	v_add_u32_e32 v115, s3, v120
	v_add_u32_e32 v128, s3, v122
	v_add_u32_e32 v130, s3, v124
	v_pk_mul_f32 v[108:109], v[162:163], v[54:55]
	v_pk_fma_f32 v[108:109], v[160:161], v[52:53], v[108:109]
	v_add_f32_e32 v229, v108, v109
	v_add_f32_dpp v178, v220, v220 row_mirror row_mask:0xf bank_mask:0x3
	v_add_f32_dpp v178, v228, v228 row_mirror row_mask:0xf bank_mask:0xc
	v_add_f32_dpp v179, v221, v221 row_mirror row_mask:0xf bank_mask:0x3
	v_add_f32_dpp v179, v229, v229 row_mirror row_mask:0xf bank_mask:0xc
	v_add_f32_dpp v181, v173, v173 row_half_mirror row_mask:0xf bank_mask:0x5
	v_add_f32_dpp v181, v177, v177 row_half_mirror row_mask:0xf bank_mask:0xa
	v_add_f32_dpp v182, v174, v174 row_half_mirror row_mask:0xf bank_mask:0x5
	v_add_f32_dpp v182, v178, v178 row_half_mirror row_mask:0xf bank_mask:0xa
	v_add_f32_dpp v183, v175, v175 row_half_mirror row_mask:0xf bank_mask:0x5
	v_add_f32_dpp v183, v179, v179 row_half_mirror row_mask:0xf bank_mask:0xa
	v_cndmask_b32_e64 v184, v180, v182, s[38:39]
	v_cndmask_b32_e64 v185, v182, v180, s[38:39]
	global_load_dwordx4 v[0:3], v112, s[96:97]
	global_load_dwordx4 v[4:7], v113, s[96:97]
	v_add_f32_dpp v186, v185, v184 quad_perm:[2,3,0,1] row_mask:0xf bank_mask:0xf bound_ctrl:1
	v_cndmask_b32_e64 v184, v181, v183, s[38:39]
	v_cndmask_b32_e64 v185, v183, v181, s[38:39]
	global_load_dwordx4 v[8:11], v114, s[96:97]
	global_load_dwordx4 v[12:15], v115, s[96:97]
	v_add_f32_dpp v187, v185, v184 quad_perm:[2,3,0,1] row_mask:0xf bank_mask:0xf bound_ctrl:1
	v_cndmask_b32_e64 v184, v186, v187, s[40:41]
	v_cndmask_b32_e64 v185, v187, v186, s[40:41]
	global_load_dwordx4 v[16:19], v128, s[96:97]
	global_load_dwordx4 v[20:23], v130, s[96:97]
	v_add_f32_dpp v110, v185, v184 quad_perm:[1,0,3,2] row_mask:0xf bank_mask:0xf bound_ctrl:1
	global_store_dword v132, v110, s[96:97]
	s_waitcnt lgkmcnt(6)
	v_pk_mul_f32 v[102:103], v[52:53], v[56:57]
	v_pk_fma_f32 v[102:103], v[54:55], v[58:59], v[102:103]
	v_pk_mul_f32 v[104:105], v[68:69], v[76:77] op_sel_hi:[1,0]
	v_add_f32_e32 v102, v102, v103
	v_pk_mul_f32 v[106:107], v[70:71], v[76:77] op_sel_hi:[1,0]
	ds_read_b128 v[136:139], v129 offset:24192
	v_add_f32_dpp v102, v102, v102 quad_perm:[1,0,3,2] row_mask:0xf bank_mask:0xf bound_ctrl:1
	v_pk_fma_f32 v[104:105], v[52:53], v[60:61], v[104:105]
	ds_read_b128 v[140:143], v129 offset:24448
	v_add_f32_dpp v102, v102, v102 quad_perm:[2,3,0,1] row_mask:0xf bank_mask:0xf bound_ctrl:1
	v_pk_fma_f32 v[106:107], v[54:55], v[62:63], v[106:107]
	ds_read_b128 v[144:147], v129 offset:24704
	v_add_f32_dpp v102, v102, v102 row_half_mirror row_mask:0xf bank_mask:0xf bound_ctrl:1
	ds_read_b128 v[148:151], v129 offset:24960
	ds_read_b128 v[152:155], v129 offset:25216
	v_add_f32_dpp v102, v102, v102 row_mirror row_mask:0xf bank_mask:0xf bound_ctrl:1
	v_pk_fma_f32 v[52:53], v[64:65], v[102:103], v[104:105] op_sel_hi:[1,0,1] neg_lo:[0,1,0] neg_hi:[0,1,0]
	v_pk_fma_f32 v[54:55], v[66:67], v[102:103], v[106:107] op_sel_hi:[1,0,1] neg_lo:[0,1,0] neg_hi:[0,1,0]
	ds_read_b32 v156, v131 offset:25472
	s_waitcnt lgkmcnt(6)
	v_pk_mul_f32 v[102:103], v[52:53], v[80:81]
	v_pk_mul_f32 v[108:109], v[74:75], v[54:55]
	v_pk_fma_f32 v[102:103], v[54:55], v[82:83], v[102:103]
	v_pk_fma_f32 v[108:109], v[72:73], v[52:53], v[108:109]
	v_pk_mul_f32 v[104:105], v[92:93], v[100:101] op_sel_hi:[1,0]
	v_add_f32_e32 v102, v102, v103
	v_add_f32_e32 v214, v108, v109
	v_pk_mul_f32 v[106:107], v[94:95], v[100:101] op_sel_hi:[1,0]
	v_add_f32_dpp v102, v102, v102 quad_perm:[1,0,3,2] row_mask:0xf bank_mask:0xf bound_ctrl:1
	v_pk_fma_f32 v[104:105], v[52:53], v[84:85], v[104:105]
	ds_read_b128 v[56:59], v129 offset:25536
	v_add_f32_dpp v102, v102, v102 quad_perm:[2,3,0,1] row_mask:0xf bank_mask:0xf bound_ctrl:1
	v_pk_fma_f32 v[106:107], v[54:55], v[86:87], v[106:107]
	ds_read_b128 v[60:63], v129 offset:25792
	v_add_f32_dpp v102, v102, v102 row_half_mirror row_mask:0xf bank_mask:0xf bound_ctrl:1
	ds_read_b128 v[64:67], v129 offset:26048
	ds_read_b128 v[68:71], v129 offset:26304
	v_add_f32_dpp v102, v102, v102 row_mirror row_mask:0xf bank_mask:0xf bound_ctrl:1
	v_pk_fma_f32 v[52:53], v[88:89], v[102:103], v[104:105] op_sel_hi:[1,0,1] neg_lo:[0,1,0] neg_hi:[0,1,0]
	v_pk_fma_f32 v[54:55], v[90:91], v[102:103], v[106:107] op_sel_hi:[1,0,1] neg_lo:[0,1,0] neg_hi:[0,1,0]
	ds_read_b128 v[72:75], v129 offset:26560
	ds_read_b32 v76, v131 offset:26816
	s_waitcnt lgkmcnt(6)
; __device__ __forceinline__ float row16_sum(float x) {
;   x = dpp_add<0xB1>(x);
;   x = dpp_add<0x4E>(x);
;   x = dpp_add<0x141>(x);
;   x = dpp_add<0x140>(x);
;   return x;
; }
	v_pk_mul_f32 v[102:103], v[52:53], v[136:137]
	v_pk_mul_f32 v[108:109], v[98:99], v[54:55]
	v_pk_fma_f32 v[102:103], v[54:55], v[138:139], v[102:103]
	v_pk_fma_f32 v[108:109], v[96:97], v[52:53], v[108:109]
	v_pk_mul_f32 v[104:105], v[148:149], v[156:157] op_sel_hi:[1,0]
	v_add_f32_e32 v102, v102, v103
	v_add_f32_e32 v215, v108, v109
	v_pk_mul_f32 v[106:107], v[150:151], v[156:157] op_sel_hi:[1,0]
	v_add_f32_dpp v102, v102, v102 quad_perm:[1,0,3,2] row_mask:0xf bank_mask:0xf bound_ctrl:1
	v_pk_fma_f32 v[104:105], v[52:53], v[140:141], v[104:105]
	ds_read_b128 v[80:83], v129 offset:26880
	v_add_f32_dpp v102, v102, v102 quad_perm:[2,3,0,1] row_mask:0xf bank_mask:0xf bound_ctrl:1
	v_pk_fma_f32 v[106:107], v[54:55], v[142:143], v[106:107]
	ds_read_b128 v[84:87], v129 offset:27136
	v_add_f32_dpp v102, v102, v102 row_half_mirror row_mask:0xf bank_mask:0xf bound_ctrl:1
	ds_read_b128 v[88:91], v129 offset:27392
	ds_read_b128 v[92:95], v129 offset:27648
	v_add_f32_dpp v102, v102, v102 row_mirror row_mask:0xf bank_mask:0xf bound_ctrl:1
	v_pk_fma_f32 v[52:53], v[144:145], v[102:103], v[104:105] op_sel_hi:[1,0,1] neg_lo:[0,1,0] neg_hi:[0,1,0]
	v_pk_fma_f32 v[54:55], v[146:147], v[102:103], v[106:107] op_sel_hi:[1,0,1] neg_lo:[0,1,0] neg_hi:[0,1,0]
	ds_read_b128 v[96:99], v129 offset:27904
	ds_read_b32 v100, v131 offset:28160
	s_waitcnt lgkmcnt(6)
	v_pk_mul_f32 v[102:103], v[52:53], v[56:57]
	v_pk_mul_f32 v[108:109], v[154:155], v[54:55]
	v_pk_fma_f32 v[102:103], v[54:55], v[58:59], v[102:103]
	v_pk_fma_f32 v[108:109], v[152:153], v[52:53], v[108:109]
	v_pk_mul_f32 v[104:105], v[68:69], v[76:77] op_sel_hi:[1,0]
	v_add_f32_e32 v102, v102, v103
	v_add_f32_e32 v216, v108, v109
	v_pk_mul_f32 v[106:107], v[70:71], v[76:77] op_sel_hi:[1,0]
	v_add_f32_dpp v102, v102, v102 quad_perm:[1,0,3,2] row_mask:0xf bank_mask:0xf bound_ctrl:1
	v_pk_fma_f32 v[104:105], v[52:53], v[60:61], v[104:105]
	ds_read_b128 v[136:139], v129 offset:28224
	v_add_f32_dpp v102, v102, v102 quad_perm:[2,3,0,1] row_mask:0xf bank_mask:0xf bound_ctrl:1
	v_pk_fma_f32 v[106:107], v[54:55], v[62:63], v[106:107]
	ds_read_b128 v[140:143], v129 offset:28480
	v_add_f32_dpp v102, v102, v102 row_half_mirror row_mask:0xf bank_mask:0xf bound_ctrl:1
	ds_read_b128 v[144:147], v129 offset:28736
	ds_read_b128 v[148:151], v129 offset:28992
	v_add_f32_dpp v102, v102, v102 row_mirror row_mask:0xf bank_mask:0xf bound_ctrl:1
	v_pk_fma_f32 v[52:53], v[64:65], v[102:103], v[104:105] op_sel_hi:[1,0,1] neg_lo:[0,1,0] neg_hi:[0,1,0]
	v_pk_fma_f32 v[54:55], v[66:67], v[102:103], v[106:107] op_sel_hi:[1,0,1] neg_lo:[0,1,0] neg_hi:[0,1,0]
	ds_read_b128 v[152:155], v129 offset:29248
	ds_read_b32 v156, v131 offset:29504
	s_waitcnt lgkmcnt(6)
	v_pk_mul_f32 v[102:103], v[52:53], v[80:81]
	v_pk_mul_f32 v[108:109], v[74:75], v[54:55]
	v_pk_fma_f32 v[102:103], v[54:55], v[82:83], v[102:103]
	v_pk_fma_f32 v[108:109], v[72:73], v[52:53], v[108:109]
	v_pk_mul_f32 v[104:105], v[92:93], v[100:101] op_sel_hi:[1,0]
	v_add_f32_e32 v102, v102, v103
	v_add_f32_e32 v217, v108, v109
	v_pk_mul_f32 v[106:107], v[94:95], v[100:101] op_sel_hi:[1,0]
	v_add_f32_dpp v102, v102, v102 quad_perm:[1,0,3,2] row_mask:0xf bank_mask:0xf bound_ctrl:1
	v_pk_fma_f32 v[104:105], v[52:53], v[84:85], v[104:105]
	ds_read_b128 v[56:59], v129 offset:29568
	v_add_f32_dpp v102, v102, v102 quad_perm:[2,3,0,1] row_mask:0xf bank_mask:0xf bound_ctrl:1
	v_pk_fma_f32 v[106:107], v[54:55], v[86:87], v[106:107]
	ds_read_b128 v[60:63], v129 offset:29824
	v_add_f32_dpp v102, v102, v102 row_half_mirror row_mask:0xf bank_mask:0xf bound_ctrl:1
	ds_read_b128 v[64:67], v129 offset:30080
	ds_read_b128 v[68:71], v129 offset:30336
	v_add_f32_dpp v102, v102, v102 row_mirror row_mask:0xf bank_mask:0xf bound_ctrl:1
	v_pk_fma_f32 v[52:53], v[88:89], v[102:103], v[104:105] op_sel_hi:[1,0,1] neg_lo:[0,1,0] neg_hi:[0,1,0]
	v_pk_fma_f32 v[54:55], v[90:91], v[102:103], v[106:107] op_sel_hi:[1,0,1] neg_lo:[0,1,0] neg_hi:[0,1,0]
	ds_read_b128 v[72:75], v129 offset:30592
	ds_read_b32 v76, v131 offset:30848
	s_waitcnt lgkmcnt(6)
	v_pk_mul_f32 v[102:103], v[52:53], v[136:137]
	v_pk_mul_f32 v[108:109], v[98:99], v[54:55]
	v_pk_fma_f32 v[102:103], v[54:55], v[138:139], v[102:103]
	v_pk_fma_f32 v[108:109], v[96:97], v[52:53], v[108:109]
	v_pk_mul_f32 v[104:105], v[148:149], v[156:157] op_sel_hi:[1,0]
	v_add_f32_e32 v102, v102, v103
	v_add_f32_e32 v218, v108, v109
	v_pk_mul_f32 v[106:107], v[150:151], v[156:157] op_sel_hi:[1,0]
	v_add_f32_dpp v102, v102, v102 quad_perm:[1,0,3,2] row_mask:0xf bank_mask:0xf bound_ctrl:1
	v_pk_fma_f32 v[104:105], v[52:53], v[140:141], v[104:105]
	ds_read_b128 v[80:83], v129 offset:30912
	v_add_f32_dpp v102, v102, v102 quad_perm:[2,3,0,1] row_mask:0xf bank_mask:0xf bound_ctrl:1
	v_pk_fma_f32 v[106:107], v[54:55], v[142:143], v[106:107]
	ds_read_b128 v[84:87], v129 offset:31168
	v_add_f32_dpp v102, v102, v102 row_half_mirror row_mask:0xf bank_mask:0xf bound_ctrl:1
	ds_read_b128 v[88:91], v129 offset:31424
	ds_read_b128 v[92:95], v129 offset:31680
	v_add_f32_dpp v102, v102, v102 row_mirror row_mask:0xf bank_mask:0xf bound_ctrl:1
	v_pk_fma_f32 v[52:53], v[144:145], v[102:103], v[104:105] op_sel_hi:[1,0,1] neg_lo:[0,1,0] neg_hi:[0,1,0]
	v_pk_fma_f32 v[54:55], v[146:147], v[102:103], v[106:107] op_sel_hi:[1,0,1] neg_lo:[0,1,0] neg_hi:[0,1,0]
	ds_read_b128 v[96:99], v129 offset:31936
	ds_read_b32 v100, v131 offset:32192
	s_waitcnt lgkmcnt(6)
	v_pk_mul_f32 v[102:103], v[52:53], v[56:57]
	v_pk_mul_f32 v[108:109], v[154:155], v[54:55]
	v_pk_fma_f32 v[102:103], v[54:55], v[58:59], v[102:103]
	v_pk_fma_f32 v[108:109], v[152:153], v[52:53], v[108:109]
	v_pk_mul_f32 v[104:105], v[68:69], v[76:77] op_sel_hi:[1,0]
	v_add_f32_e32 v102, v102, v103
	v_add_f32_e32 v219, v108, v109
	v_pk_mul_f32 v[106:107], v[70:71], v[76:77] op_sel_hi:[1,0]
	v_add_f32_dpp v102, v102, v102 quad_perm:[1,0,3,2] row_mask:0xf bank_mask:0xf bound_ctrl:1
	v_pk_fma_f32 v[104:105], v[52:53], v[60:61], v[104:105]
	ds_read_b128 v[136:139], v129 offset:32256
	v_add_f32_dpp v102, v102, v102 quad_perm:[2,3,0,1] row_mask:0xf bank_mask:0xf bound_ctrl:1
	v_pk_fma_f32 v[106:107], v[54:55], v[62:63], v[106:107]
	ds_read_b128 v[140:143], v129 offset:32512
	v_add_f32_dpp v102, v102, v102 row_half_mirror row_mask:0xf bank_mask:0xf bound_ctrl:1
	ds_read_b128 v[144:147], v129 offset:32768
	ds_read_b128 v[148:151], v129 offset:33024
	v_add_f32_dpp v102, v102, v102 row_mirror row_mask:0xf bank_mask:0xf bound_ctrl:1
	v_pk_fma_f32 v[52:53], v[64:65], v[102:103], v[104:105] op_sel_hi:[1,0,1] neg_lo:[0,1,0] neg_hi:[0,1,0]
	v_pk_fma_f32 v[54:55], v[66:67], v[102:103], v[106:107] op_sel_hi:[1,0,1] neg_lo:[0,1,0] neg_hi:[0,1,0]
	ds_read_b128 v[152:155], v129 offset:33280
	ds_read_b32 v156, v131 offset:33536
	s_waitcnt lgkmcnt(6)
	v_pk_mul_f32 v[102:103], v[52:53], v[80:81]
	v_pk_mul_f32 v[108:109], v[74:75], v[54:55]
	v_pk_fma_f32 v[102:103], v[54:55], v[82:83], v[102:103]
	v_pk_fma_f32 v[108:109], v[72:73], v[52:53], v[108:109]
	v_pk_mul_f32 v[104:105], v[92:93], v[100:101] op_sel_hi:[1,0]
	v_add_f32_e32 v102, v102, v103
	v_add_f32_e32 v220, v108, v109
	v_pk_mul_f32 v[106:107], v[94:95], v[100:101] op_sel_hi:[1,0]
	v_add_f32_dpp v102, v102, v102 quad_perm:[1,0,3,2] row_mask:0xf bank_mask:0xf bound_ctrl:1
	v_pk_fma_f32 v[104:105], v[52:53], v[84:85], v[104:105]
	ds_read_b128 v[56:59], v129 offset:33600
	v_add_f32_dpp v102, v102, v102 quad_perm:[2,3,0,1] row_mask:0xf bank_mask:0xf bound_ctrl:1
	v_pk_fma_f32 v[106:107], v[54:55], v[86:87], v[106:107]
	ds_read_b128 v[60:63], v129 offset:33856
	v_add_f32_dpp v102, v102, v102 row_half_mirror row_mask:0xf bank_mask:0xf bound_ctrl:1
	ds_read_b128 v[64:67], v129 offset:34112
	ds_read_b128 v[68:71], v129 offset:34368
	v_add_f32_dpp v102, v102, v102 row_mirror row_mask:0xf bank_mask:0xf bound_ctrl:1
	v_pk_fma_f32 v[52:53], v[88:89], v[102:103], v[104:105] op_sel_hi:[1,0,1] neg_lo:[0,1,0] neg_hi:[0,1,0]
	v_pk_fma_f32 v[54:55], v[90:91], v[102:103], v[106:107] op_sel_hi:[1,0,1] neg_lo:[0,1,0] neg_hi:[0,1,0]
	ds_read_b128 v[72:75], v129 offset:34624
	ds_read_b32 v76, v131 offset:34880
	s_waitcnt lgkmcnt(6)
	v_pk_mul_f32 v[102:103], v[52:53], v[136:137]
	v_pk_mul_f32 v[108:109], v[98:99], v[54:55]
	v_pk_fma_f32 v[102:103], v[54:55], v[138:139], v[102:103]
	v_pk_fma_f32 v[108:109], v[96:97], v[52:53], v[108:109]
	v_pk_mul_f32 v[104:105], v[148:149], v[156:157] op_sel_hi:[1,0]
	v_add_f32_e32 v102, v102, v103
	v_add_f32_e32 v221, v108, v109
	v_pk_mul_f32 v[106:107], v[150:151], v[156:157] op_sel_hi:[1,0]
	v_add_f32_dpp v102, v102, v102 quad_perm:[1,0,3,2] row_mask:0xf bank_mask:0xf bound_ctrl:1
	v_pk_fma_f32 v[104:105], v[52:53], v[140:141], v[104:105]
	ds_read_b128 v[80:83], v129 offset:34944
	v_add_f32_dpp v102, v102, v102 quad_perm:[2,3,0,1] row_mask:0xf bank_mask:0xf bound_ctrl:1
	v_pk_fma_f32 v[106:107], v[54:55], v[142:143], v[106:107]
	ds_read_b128 v[84:87], v129 offset:35200
	v_add_f32_dpp v102, v102, v102 row_half_mirror row_mask:0xf bank_mask:0xf bound_ctrl:1
	ds_read_b128 v[88:91], v129 offset:35456
	ds_read_b128 v[92:95], v129 offset:35712
	v_add_f32_dpp v102, v102, v102 row_mirror row_mask:0xf bank_mask:0xf bound_ctrl:1
	v_pk_fma_f32 v[52:53], v[144:145], v[102:103], v[104:105] op_sel_hi:[1,0,1] neg_lo:[0,1,0] neg_hi:[0,1,0]
	v_pk_fma_f32 v[54:55], v[146:147], v[102:103], v[106:107] op_sel_hi:[1,0,1] neg_lo:[0,1,0] neg_hi:[0,1,0]
	ds_read_b128 v[96:99], v129 offset:35968
	ds_read_b32 v100, v131 offset:36224
	s_waitcnt vmcnt(11)
	ds_write_b128 v117, v[28:31]
	s_waitcnt lgkmcnt(7)
	v_pk_mul_f32 v[102:103], v[52:53], v[56:57]
	v_pk_mul_f32 v[108:109], v[154:155], v[54:55]
	v_pk_fma_f32 v[102:103], v[54:55], v[58:59], v[102:103]
	v_pk_fma_f32 v[108:109], v[152:153], v[52:53], v[108:109]
	v_pk_mul_f32 v[104:105], v[68:69], v[76:77] op_sel_hi:[1,0]
	v_add_f32_e32 v102, v102, v103
	v_add_f32_e32 v222, v108, v109
	v_pk_mul_f32 v[106:107], v[70:71], v[76:77] op_sel_hi:[1,0]
	v_add_f32_dpp v102, v102, v102 quad_perm:[1,0,3,2] row_mask:0xf bank_mask:0xf bound_ctrl:1
	v_pk_fma_f32 v[104:105], v[52:53], v[60:61], v[104:105]
	ds_read_b128 v[136:139], v129 offset:36288
	v_add_f32_dpp v102, v102, v102 quad_perm:[2,3,0,1] row_mask:0xf bank_mask:0xf bound_ctrl:1
	v_pk_fma_f32 v[106:107], v[54:55], v[62:63], v[106:107]
	ds_read_b128 v[140:143], v129 offset:36544
	v_add_f32_dpp v102, v102, v102 row_half_mirror row_mask:0xf bank_mask:0xf bound_ctrl:1
	ds_read_b128 v[144:147], v129 offset:36800
	ds_read_b128 v[148:151], v129 offset:37056
	v_add_f32_dpp v102, v102, v102 row_mirror row_mask:0xf bank_mask:0xf bound_ctrl:1
	v_pk_fma_f32 v[52:53], v[64:65], v[102:103], v[104:105] op_sel_hi:[1,0,1] neg_lo:[0,1,0] neg_hi:[0,1,0]
	v_pk_fma_f32 v[54:55], v[66:67], v[102:103], v[106:107] op_sel_hi:[1,0,1] neg_lo:[0,1,0] neg_hi:[0,1,0]
	ds_read_b128 v[152:155], v129 offset:37312
	ds_read_b32 v156, v131 offset:37568
	s_waitcnt vmcnt(10)
	ds_write_b128 v119, v[32:35]
	s_waitcnt lgkmcnt(8)
	v_pk_mul_f32 v[102:103], v[52:53], v[80:81]
	v_pk_mul_f32 v[108:109], v[74:75], v[54:55]
	v_pk_fma_f32 v[102:103], v[54:55], v[82:83], v[102:103]
	v_pk_fma_f32 v[108:109], v[72:73], v[52:53], v[108:109]
	v_pk_mul_f32 v[104:105], v[92:93], v[100:101] op_sel_hi:[1,0]
	v_add_f32_e32 v102, v102, v103
	v_add_f32_e32 v223, v108, v109
	v_pk_mul_f32 v[106:107], v[94:95], v[100:101] op_sel_hi:[1,0]
	v_add_f32_dpp v102, v102, v102 quad_perm:[1,0,3,2] row_mask:0xf bank_mask:0xf bound_ctrl:1
	v_pk_fma_f32 v[104:105], v[52:53], v[84:85], v[104:105]
	v_add_f32_dpp v172, v214, v214 row_mirror row_mask:0xf bank_mask:0x3
	v_add_f32_dpp v102, v102, v102 quad_perm:[2,3,0,1] row_mask:0xf bank_mask:0xf bound_ctrl:1
	v_pk_fma_f32 v[106:107], v[54:55], v[86:87], v[106:107]
	v_add_f32_dpp v172, v222, v222 row_mirror row_mask:0xf bank_mask:0xc
	v_add_f32_dpp v102, v102, v102 row_half_mirror row_mask:0xf bank_mask:0xf bound_ctrl:1
	ds_read_b128 v[56:59], v129 offset:37632
	ds_read_b128 v[60:63], v129 offset:37888
	v_add_f32_dpp v102, v102, v102 row_mirror row_mask:0xf bank_mask:0xf bound_ctrl:1
	v_pk_fma_f32 v[52:53], v[88:89], v[102:103], v[104:105] op_sel_hi:[1,0,1] neg_lo:[0,1,0] neg_hi:[0,1,0]
	v_pk_fma_f32 v[54:55], v[90:91], v[102:103], v[106:107] op_sel_hi:[1,0,1] neg_lo:[0,1,0] neg_hi:[0,1,0]
	ds_read_b128 v[64:67], v129 offset:38144
	ds_read_b128 v[68:71], v129 offset:38400
	ds_read_b128 v[72:75], v129 offset:38656
	ds_read_b32 v76, v131 offset:38912
	s_waitcnt vmcnt(9)
	ds_write_b128 v121, v[36:39]
	s_waitcnt lgkmcnt(8)
	v_pk_mul_f32 v[102:103], v[52:53], v[136:137]
	v_pk_mul_f32 v[108:109], v[98:99], v[54:55]
	v_pk_fma_f32 v[102:103], v[54:55], v[138:139], v[102:103]
	v_pk_fma_f32 v[108:109], v[96:97], v[52:53], v[108:109]
	v_pk_mul_f32 v[104:105], v[148:149], v[156:157] op_sel_hi:[1,0]
	v_add_f32_e32 v102, v102, v103
	v_add_f32_e32 v224, v108, v109
	v_pk_mul_f32 v[106:107], v[150:151], v[156:157] op_sel_hi:[1,0]
	v_add_f32_dpp v102, v102, v102 quad_perm:[1,0,3,2] row_mask:0xf bank_mask:0xf bound_ctrl:1
	v_pk_fma_f32 v[104:105], v[52:53], v[140:141], v[104:105]
	v_add_f32_dpp v173, v215, v215 row_mirror row_mask:0xf bank_mask:0x3
	v_add_f32_dpp v102, v102, v102 quad_perm:[2,3,0,1] row_mask:0xf bank_mask:0xf bound_ctrl:1
	v_pk_fma_f32 v[106:107], v[54:55], v[142:143], v[106:107]
	v_add_f32_dpp v173, v223, v223 row_mirror row_mask:0xf bank_mask:0xc
	v_add_f32_dpp v102, v102, v102 row_half_mirror row_mask:0xf bank_mask:0xf bound_ctrl:1
	ds_read_b128 v[80:83], v129 offset:38976
	ds_read_b128 v[84:87], v129 offset:39232
	v_add_f32_dpp v102, v102, v102 row_mirror row_mask:0xf bank_mask:0xf bound_ctrl:1
	v_pk_fma_f32 v[52:53], v[144:145], v[102:103], v[104:105] op_sel_hi:[1,0,1] neg_lo:[0,1,0] neg_hi:[0,1,0]
	v_pk_fma_f32 v[54:55], v[146:147], v[102:103], v[106:107] op_sel_hi:[1,0,1] neg_lo:[0,1,0] neg_hi:[0,1,0]
	ds_read_b128 v[88:91], v129 offset:39488
	ds_read_b128 v[92:95], v129 offset:39744
	ds_read_b128 v[96:99], v129 offset:40000
	ds_read_b32 v100, v131 offset:40256
	s_waitcnt vmcnt(8)
	ds_write_b128 v123, v[40:43]
	s_waitcnt lgkmcnt(8)
	v_pk_mul_f32 v[102:103], v[52:53], v[56:57]
	v_pk_mul_f32 v[108:109], v[154:155], v[54:55]
	v_pk_fma_f32 v[102:103], v[54:55], v[58:59], v[102:103]
	v_pk_fma_f32 v[108:109], v[152:153], v[52:53], v[108:109]
	v_pk_mul_f32 v[104:105], v[68:69], v[76:77] op_sel_hi:[1,0]
	v_add_f32_e32 v102, v102, v103
	v_add_f32_e32 v225, v108, v109
	v_pk_mul_f32 v[106:107], v[70:71], v[76:77] op_sel_hi:[1,0]
	v_add_f32_dpp v102, v102, v102 quad_perm:[1,0,3,2] row_mask:0xf bank_mask:0xf bound_ctrl:1
	v_pk_fma_f32 v[104:105], v[52:53], v[60:61], v[104:105]
	v_add_f32_dpp v174, v216, v216 row_mirror row_mask:0xf bank_mask:0x3
	v_add_f32_dpp v102, v102, v102 quad_perm:[2,3,0,1] row_mask:0xf bank_mask:0xf bound_ctrl:1
	v_pk_fma_f32 v[106:107], v[54:55], v[62:63], v[106:107]
	v_add_f32_dpp v174, v224, v224 row_mirror row_mask:0xf bank_mask:0xc
	v_add_f32_dpp v102, v102, v102 row_half_mirror row_mask:0xf bank_mask:0xf bound_ctrl:1
	ds_read_b128 v[136:139], v129 offset:40320
	ds_read_b128 v[140:143], v129 offset:40576
	v_add_f32_dpp v102, v102, v102 row_mirror row_mask:0xf bank_mask:0xf bound_ctrl:1
	v_pk_fma_f32 v[52:53], v[64:65], v[102:103], v[104:105] op_sel_hi:[1,0,1] neg_lo:[0,1,0] neg_hi:[0,1,0]
	v_pk_fma_f32 v[54:55], v[66:67], v[102:103], v[106:107] op_sel_hi:[1,0,1] neg_lo:[0,1,0] neg_hi:[0,1,0]
	ds_read_b128 v[144:147], v129 offset:40832
	ds_read_b128 v[148:151], v129 offset:41088
	ds_read_b128 v[152:155], v129 offset:41344
	ds_read_b32 v156, v131 offset:41600
	s_waitcnt vmcnt(7)
	ds_write_b128 v125, v[44:47]
	s_waitcnt lgkmcnt(8)
	v_pk_mul_f32 v[102:103], v[52:53], v[80:81]
	v_pk_mul_f32 v[108:109], v[74:75], v[54:55]
	v_pk_fma_f32 v[102:103], v[54:55], v[82:83], v[102:103]
	v_pk_fma_f32 v[108:109], v[72:73], v[52:53], v[108:109]
	v_pk_mul_f32 v[104:105], v[92:93], v[100:101] op_sel_hi:[1,0]
	v_add_f32_e32 v102, v102, v103
	v_add_f32_e32 v226, v108, v109
	v_pk_mul_f32 v[106:107], v[94:95], v[100:101] op_sel_hi:[1,0]
	v_add_f32_dpp v102, v102, v102 quad_perm:[1,0,3,2] row_mask:0xf bank_mask:0xf bound_ctrl:1
	v_pk_fma_f32 v[104:105], v[52:53], v[84:85], v[104:105]
	v_add_f32_dpp v175, v217, v217 row_mirror row_mask:0xf bank_mask:0x3
	v_add_f32_dpp v102, v102, v102 quad_perm:[2,3,0,1] row_mask:0xf bank_mask:0xf bound_ctrl:1
	v_pk_fma_f32 v[106:107], v[54:55], v[86:87], v[106:107]
	v_add_f32_dpp v175, v225, v225 row_mirror row_mask:0xf bank_mask:0xc
	v_add_f32_dpp v102, v102, v102 row_half_mirror row_mask:0xf bank_mask:0xf bound_ctrl:1
	ds_read_b128 v[56:59], v129 offset:41664
	ds_read_b128 v[60:63], v129 offset:41920
	v_add_f32_dpp v102, v102, v102 row_mirror row_mask:0xf bank_mask:0xf bound_ctrl:1
	v_pk_fma_f32 v[52:53], v[88:89], v[102:103], v[104:105] op_sel_hi:[1,0,1] neg_lo:[0,1,0] neg_hi:[0,1,0]
	v_pk_fma_f32 v[54:55], v[90:91], v[102:103], v[106:107] op_sel_hi:[1,0,1] neg_lo:[0,1,0] neg_hi:[0,1,0]
	ds_read_b128 v[64:67], v129 offset:42176
	ds_read_b128 v[68:71], v129 offset:42432
	ds_read_b128 v[160:163], v129 offset:42688
	ds_read_b32 v76, v131 offset:42944
	s_waitcnt vmcnt(6)
; #define LBAR() asm volatile("s_waitcnt lgkmcnt(0)\n\ts_barrier" ::: "memory")
; #define SC_STORE(R, B)                                                \
;   _Pragma("unroll") for (int i = 0; i < 6; ++i) *(f32x4*)(buf + (B) * SC_CH * SC_STEPF + pf[i]) = R[i];
; __device__ __forceinline__ void scan_unit(const Params p, int u, char* smem) {
;     ...
;   __syncthreads();
;   __builtin_amdgcn_s_setprio(3);
;   SC_LOAD(lregA, 0);
;   SC_STORE(lregA, 0);
;   SC_LOAD(lregB, 1);
;   __syncthreads();
;   for (int c = 0; c < nch; c += 2) {
;     SC_LOAD(lregA, c + 2);
;     SC_COMPUTE(c, 0);
;     SC_STORE(lregB, 1);
;     LBAR();
;     SC_LOAD(lregB, c + 3);
;     SC_COMPUTE(c + 1, 1);
;     SC_STORE(lregA, 0);
;     LBAR();
;   }
;   __builtin_amdgcn_s_setprio(0);
; }
; template <int ATM>
; __device__ __forceinline__ void phase_attn_scan(const Params p, int l, char* smem) {
;   char* ws = p.ws;
;   __shared__ int s_item;
;   if (ATM & 8) for (int u = lbid(); u < 64; u += gridDim.x) scan_unit(p, u, smem);
	ds_write_b128 v127, v[24:27]
	s_waitcnt lgkmcnt(8)
	v_pk_mul_f32 v[102:103], v[52:53], v[136:137]
	v_pk_mul_f32 v[108:109], v[98:99], v[54:55]
	v_pk_fma_f32 v[102:103], v[54:55], v[138:139], v[102:103]
	v_pk_fma_f32 v[108:109], v[96:97], v[52:53], v[108:109]
	v_pk_mul_f32 v[104:105], v[148:149], v[156:157] op_sel_hi:[1,0]
	v_add_f32_e32 v102, v102, v103
	v_add_f32_e32 v227, v108, v109
	v_pk_mul_f32 v[106:107], v[150:151], v[156:157] op_sel_hi:[1,0]
	v_add_f32_dpp v102, v102, v102 quad_perm:[1,0,3,2] row_mask:0xf bank_mask:0xf bound_ctrl:1
	v_pk_fma_f32 v[104:105], v[52:53], v[140:141], v[104:105]
	v_add_f32_dpp v176, v218, v218 row_mirror row_mask:0xf bank_mask:0x3
	v_add_f32_dpp v102, v102, v102 quad_perm:[2,3,0,1] row_mask:0xf bank_mask:0xf bound_ctrl:1
	v_pk_fma_f32 v[106:107], v[54:55], v[142:143], v[106:107]
	v_add_f32_dpp v176, v226, v226 row_mirror row_mask:0xf bank_mask:0xc
	v_add_f32_dpp v102, v102, v102 row_half_mirror row_mask:0xf bank_mask:0xf bound_ctrl:1
	s_nop 0
	s_nop 0
	v_add_f32_dpp v102, v102, v102 row_mirror row_mask:0xf bank_mask:0xf bound_ctrl:1
	v_pk_fma_f32 v[52:53], v[144:145], v[102:103], v[104:105] op_sel_hi:[1,0,1] neg_lo:[0,1,0] neg_hi:[0,1,0]
	v_pk_fma_f32 v[54:55], v[146:147], v[102:103], v[106:107] op_sel_hi:[1,0,1] neg_lo:[0,1,0] neg_hi:[0,1,0]
	s_waitcnt lgkmcnt(1)
	v_pk_mul_f32 v[102:103], v[52:53], v[56:57]
	v_pk_mul_f32 v[108:109], v[154:155], v[54:55]
	v_pk_fma_f32 v[102:103], v[54:55], v[58:59], v[102:103]
	v_pk_fma_f32 v[108:109], v[152:153], v[52:53], v[108:109]
	v_pk_mul_f32 v[104:105], v[68:69], v[76:77] op_sel_hi:[1,0]
	v_add_f32_e32 v102, v102, v103
	v_add_f32_e32 v228, v108, v109
	v_pk_mul_f32 v[106:107], v[70:71], v[76:77] op_sel_hi:[1,0]
	v_add_f32_dpp v102, v102, v102 quad_perm:[1,0,3,2] row_mask:0xf bank_mask:0xf bound_ctrl:1
	v_pk_fma_f32 v[104:105], v[52:53], v[60:61], v[104:105]
	v_add_f32_dpp v177, v219, v219 row_mirror row_mask:0xf bank_mask:0x3
	v_add_f32_dpp v102, v102, v102 quad_perm:[2,3,0,1] row_mask:0xf bank_mask:0xf bound_ctrl:1
	v_pk_fma_f32 v[106:107], v[54:55], v[62:63], v[106:107]
	v_add_f32_dpp v177, v227, v227 row_mirror row_mask:0xf bank_mask:0xc
	v_add_f32_dpp v102, v102, v102 row_half_mirror row_mask:0xf bank_mask:0xf bound_ctrl:1
	v_add_f32_dpp v180, v172, v172 row_half_mirror row_mask:0xf bank_mask:0x5
	s_nop 0
	v_add_f32_dpp v102, v102, v102 row_mirror row_mask:0xf bank_mask:0xf bound_ctrl:1
	v_add_f32_dpp v180, v176, v176 row_half_mirror row_mask:0xf bank_mask:0xa
	v_pk_fma_f32 v[52:53], v[64:65], v[102:103], v[104:105] op_sel_hi:[1,0,1] neg_lo:[0,1,0] neg_hi:[0,1,0]
	v_pk_fma_f32 v[54:55], v[66:67], v[102:103], v[106:107] op_sel_hi:[1,0,1] neg_lo:[0,1,0] neg_hi:[0,1,0]
	v_add_u32_e32 v111, s0, v132
	v_add_u32_e32 v132, s1, v132
	s_mov_b32 s3, s2
	s_cmpk_lt_u32 s2, 0x1fe
	s_waitcnt lgkmcnt(0)
	s_barrier
	s_cbranch_scc1 .LBB0_99
	v_pk_mul_f32 v[108:109], v[162:163], v[54:55]
	v_pk_fma_f32 v[108:109], v[160:161], v[52:53], v[108:109]
	v_add_f32_e32 v229, v108, v109
	v_add_f32_dpp v178, v220, v220 row_mirror row_mask:0xf bank_mask:0x3
	v_add_f32_dpp v178, v228, v228 row_mirror row_mask:0xf bank_mask:0xc
	v_add_f32_dpp v179, v221, v221 row_mirror row_mask:0xf bank_mask:0x3
	v_add_f32_dpp v179, v229, v229 row_mirror row_mask:0xf bank_mask:0xc
	v_add_f32_dpp v181, v173, v173 row_half_mirror row_mask:0xf bank_mask:0x5
	v_add_f32_dpp v181, v177, v177 row_half_mirror row_mask:0xf bank_mask:0xa
	v_add_f32_dpp v182, v174, v174 row_half_mirror row_mask:0xf bank_mask:0x5
	v_add_f32_dpp v182, v178, v178 row_half_mirror row_mask:0xf bank_mask:0xa
	v_add_f32_dpp v183, v175, v175 row_half_mirror row_mask:0xf bank_mask:0x5
	v_add_f32_dpp v183, v179, v179 row_half_mirror row_mask:0xf bank_mask:0xa
	v_cndmask_b32_e64 v184, v180, v182, s[38:39]
	v_cndmask_b32_e64 v185, v182, v180, s[38:39]
	s_nop 0
	s_nop 0
	v_add_f32_dpp v186, v185, v184 quad_perm:[2,3,0,1] row_mask:0xf bank_mask:0xf bound_ctrl:1
	v_cndmask_b32_e64 v184, v181, v183, s[38:39]
	v_cndmask_b32_e64 v185, v183, v181, s[38:39]
	s_nop 0
	s_nop 0
	v_add_f32_dpp v187, v185, v184 quad_perm:[2,3,0,1] row_mask:0xf bank_mask:0xf bound_ctrl:1
	v_cndmask_b32_e64 v184, v186, v187, s[40:41]
	v_cndmask_b32_e64 v185, v187, v186, s[40:41]
	s_nop 0
	s_nop 0
	v_add_f32_dpp v110, v185, v184 quad_perm:[1,0,3,2] row_mask:0xf bank_mask:0xf bound_ctrl:1
	global_store_dword v111, v110, s[96:97]
	s_waitcnt vmcnt(0)
	s_setprio 0
	v_readlane_b32 s52, v244, 4
	v_readlane_b32 s0, v245, 54
	v_readlane_b32 s56, v244, 8
	v_readlane_b32 s57, v244, 9
	v_readlane_b32 s58, v244, 10
	v_readlane_b32 s59, v244, 11
	v_readlane_b32 s60, v244, 12
	v_readlane_b32 s61, v244, 13
	v_readlane_b32 s62, v244, 14
	v_readlane_b32 s63, v244, 15
	v_readlane_b32 s64, v244, 16
	v_readlane_b32 s65, v244, 17
	s_add_i32 s70, s70, s86
	s_add_i32 s72, s72, s0
	v_readlane_b32 s66, v244, 18
	v_readlane_b32 s67, v244, 19
	v_readlane_b32 s56, v244, 21
	v_readlane_b32 s58, v244, 23
	v_readlane_b32 s60, v244, 25
	v_readlane_b32 s62, v244, 27
	v_readlane_b32 s64, v244, 29
	s_cmp_gt_i32 s70, 63
	v_readlane_b32 s53, v244, 5
	v_readlane_b32 s54, v244, 6
	v_readlane_b32 s55, v244, 7
	v_readlane_b32 s57, v244, 22
	v_readlane_b32 s59, v244, 24
	v_readlane_b32 s61, v244, 26
	v_readlane_b32 s63, v244, 28
	v_readlane_b32 s65, v244, 30
	v_readlane_b32 s66, v244, 31
	v_readlane_b32 s67, v244, 32
	v_readlane_b32 s50, v244, 33
	s_movk_i32 s51, 0x3ff
	v_readlane_b32 s48, v244, 34
	s_cbranch_scc0 .LBB0_62
	v_readlane_b32 s72, v244, 20
	s_branch .LBB0_248

; __device__ __forceinline__ bool tile_map2(int t, int NT, int& mt, int& nt) {
;   if (gridDim.x == 512) {
;     int bid = t & 511, k = t >> 9, x = bid & 7, j = bid >> 3;
;     mt = 4 * x + (j & 3);
;     nt = 16 * k + (j >> 2);
;   } else {
;     mt = t & 31;
;     nt = t >> 5;
;   }
;   return nt < NT;
; }
.LBB0_506:
	s_lshl_b32 s0, s37, 2
	s_and_b32 s0, s0, 28
	s_bfe_u32 s1, s37, 0x10003
	s_lshl_b32 s1, s1, 1
	s_or_b32 s0, s0, s1
	s_bfe_u32 s1, s37, 0x10008
	s_or_b32 s38, s0, s1
	s_ashr_i32 s0, s37, 5
	s_and_b32 s0, s0, -16
	s_bfe_u32 s1, s37, 0x40004
	s_or_b32 s0, s0, s1
	s_cmpk_gt_i32 s0, 0x6f
	s_cbranch_scc1 .LBB0_501
